# as v40 but the hoisted DMA pair is issued after the epilogue's row-statistic wait (still ahead of all epilogue stores)
# speedup vs baseline: 1.0008x; 1.0008x over previous
; __device__ __forceinline__ float ld_agent(const rss_t* p) { return (float)__hip_atomic_load(p, __ATOMIC_RELAXED, __HIP_MEMORY_SCOPE_AGENT) * (1.0f / 16777216.0f); }
; __device__ __forceinline__ rss_t rss_fix(float ss) { return (rss_t)(ss * 16777216.0f); }
; __device__ __forceinline__ float rstd_of(const rss_t* rowss, int row) { return __builtin_amdgcn_rsqf(ld_agent(rowss + row) * (1.0f / 1024.0f) + 1e-6f); }
; __device__ __forceinline__ unsigned silu_pk(f32x2 g, f32x2 u, float k1, float k2) {
;     const f32x2 t = g * k1; f32x2 ex; ex.x = __builtin_amdgcn_exp2f(t.x); ex.y = __builtin_amdgcn_exp2f(t.y);
;     const f32x2 d = ex + 1.0f; f32x2 r; r.x = __builtin_amdgcn_rcpf(d.x); r.y = __builtin_amdgcn_rcpf(d.y);
;     const f32x2 o = (g * u) * (r * k2);
;     return cvt_pk_bf16(o.x, o.y);
; }
; __device__ __forceinline__ float silu_mul(float g, float u) { return g * __builtin_amdgcn_rcpf(1.0f + __builtin_amdgcn_exp2f(-1.4426950408889634f * g)) * u; }
;     __device__ __forceinline__ void operator()(const f32x4 (&acc)[2][2][4][2], const Unit& u, int wr, int wc, int fr, int fq) const {
;         const int row0 = u.pm * BM + wr * 64 + fr, col0 = u.pn * HALF + wc * 32 + 8 * fq;
;         float ssq[2][4];
; #pragma unroll
;         for (int ai = 0; ai < 2; ++ai)
; #pragma unroll
;             for (int m = 0; m < 4; ++m) ssq[ai][m] = ld_agent(rowss + row0 + ai * HALF + m * 16);
; #pragma unroll
;         for (int ai = 0; ai < 2; ++ai)
; #pragma unroll
;             for (int m = 0; m < 4; ++m) {
;                 const int row = row0 + ai * HALF + m * 16; const float rs = __builtin_amdgcn_rsqf(ssq[ai][m] * (1.0f / 1024.0f) + 1e-6f);
;                 const float k1 = -1.4426950408889634f * rs, k2 = rs * rs;
;                 u32x4 w;
; #pragma unroll
;                 for (int n = 0; n < 2; ++n) {
;                     const f32x4 gv = acc[ai][0][m][n], uv = acc[ai][1][m][n];
;                     const unsigned lo = silu_pk((f32x2){gv[0], gv[1]}, (f32x2){uv[0], uv[1]}, k1, k2), hi = silu_pk((f32x2){gv[2], gv[3]}, (f32x2){uv[2], uv[3]}, k1, k2);
; template <class Epi, class Sched, bool ALIGN_EPI = false, bool SP2 = false>
; __device__ __forceinline__ void gemm_phase(PG8_LAS unsigned char* lds, const Gemm g, const Sched& S, const Epi& E) {
;     ...
;             PG8_LDB(B0, 0, 0); PG8_LDB(B1, 0, 1); PG8_SCHED; PG8_LDA(At, 0, 0); PG8_STAGE(PG8_SA(1, 1), a1 + hstep, voffA);
.LBB0_235:
	v_lshl_add_u32 v144, s36, 8, v146
	v_ashrrev_i32_e32 v145, 31, v144
	v_lshl_add_u64 v[154:155], v[144:145], 3, s[8:9]
	global_load_dwordx2 v[156:157], v[154:155], off sc1
	global_load_dwordx2 v[158:159], v[154:155], off offset:128 sc1
	global_load_dwordx2 v[160:161], v[154:155], off offset:256 sc1
	global_load_dwordx2 v[162:163], v[154:155], off offset:384 sc1
	global_load_dwordx2 v[164:165], v[154:155], off offset:1024 sc1
	global_load_dwordx2 v[166:167], v[154:155], off offset:1152 sc1
	global_load_dwordx2 v[168:169], v[154:155], off offset:1280 sc1
	s_nop 0
	global_load_dwordx2 v[154:155], v[154:155], off offset:1408 sc1
	v_pk_mul_f32 v[172:173], v[120:121], v[124:125]
	v_pk_mul_f32 v[126:127], v[122:123], v[126:127]
	v_pk_mul_f32 v[112:113], v[116:117], v[112:113]
	v_pk_mul_f32 v[114:115], v[118:119], v[114:115]
	v_lshl_or_b32 v170, s63, 7, v148
	v_ashrrev_i32_e32 v171, 31, v170
	v_pk_mul_f32 v[104:105], v[108:109], v[104:105]
	v_pk_mul_f32 v[106:107], v[110:111], v[106:107]
	v_pk_mul_f32 v[96:97], v[100:101], v[96:97]
	v_pk_mul_f32 v[98:99], v[102:103], v[98:99]
	v_pk_mul_f32 v[88:89], v[92:93], v[88:89]
	v_pk_mul_f32 v[90:91], v[94:95], v[90:91]
	v_pk_mul_f32 v[80:81], v[84:85], v[80:81]
	v_pk_mul_f32 v[82:83], v[86:87], v[82:83]
	v_pk_mul_f32 v[72:73], v[76:77], v[72:73]
	v_pk_mul_f32 v[74:75], v[78:79], v[74:75]
	v_pk_mul_f32 v[64:65], v[68:69], v[64:65]
	v_pk_mul_f32 v[66:67], v[70:71], v[66:67]
	v_pk_mul_f32 v[56:57], v[60:61], v[56:57]
	v_pk_mul_f32 v[58:59], v[62:63], v[58:59]
	v_pk_mul_f32 v[48:49], v[52:53], v[48:49]
	v_pk_mul_f32 v[50:51], v[54:55], v[50:51]
	v_pk_mul_f32 v[40:41], v[44:45], v[40:41]
	v_pk_mul_f32 v[42:43], v[46:47], v[42:43]
	v_pk_mul_f32 v[32:33], v[36:37], v[32:33]
	v_pk_mul_f32 v[34:35], v[38:39], v[34:35]
	v_pk_mul_f32 v[24:25], v[28:29], v[24:25]
	v_pk_mul_f32 v[26:27], v[30:31], v[26:27]
	v_pk_mul_f32 v[16:17], v[20:21], v[16:17]
	v_pk_mul_f32 v[18:19], v[22:23], v[18:19]
	v_pk_mul_f32 v[8:9], v[12:13], v[8:9]
	v_pk_mul_f32 v[10:11], v[14:15], v[10:11]
	v_pk_mul_f32 v[0:1], v[4:5], v[0:1]
	v_pk_mul_f32 v[2:3], v[6:7], v[2:3]
	s_andn2_b64 vcc, exec, s[4:5]
	s_mov_b64 s[4:5], -1
	s_waitcnt vmcnt(0)
	s_cbranch_vccnz .Lhoist_skip_0
	s_add_u32 s96, s22, 0x40080
	s_addc_u32 s97, s23, 0
	v_lshl_add_u64 v[224:225], s[96:97], 0, v[136:137]
	s_add_i32 m0, s37, 0xc000
	s_nop 0
	global_load_lds_dwordx4 v[224:225], off
	v_lshl_add_u64 v[224:225], s[96:97], 0, v[138:139]
	s_add_i32 m0, s37, 0xe000
	s_nop 0
	global_load_lds_dwordx4 v[224:225], off
.Lhoist_skip_0:
	v_ffbh_u32_e32 v124, v157
	v_ffbh_u32_e32 v125, v159
	v_min_u32_e32 v178, 32, v124
	v_min_u32_e32 v179, 32, v125
	v_lshlrev_b64 v[124:125], v178, v[156:157]
	v_ffbh_u32_e32 v145, v161
	v_ffbh_u32_e32 v153, v163
	v_ffbh_u32_e32 v174, v165
	v_ffbh_u32_e32 v175, v167
	v_min_u32_e32 v124, 1, v124
	v_ffbh_u32_e32 v177, v155
	v_min_u32_e32 v145, 32, v145
	v_min_u32_e32 v153, 32, v153
	v_min_u32_e32 v174, 32, v174
	v_min_u32_e32 v175, 32, v175
	v_or_b32_e32 v124, v125, v124
	v_min_u32_e32 v177, 32, v177
	v_lshlrev_b64 v[156:157], v179, v[158:159]
	v_lshlrev_b64 v[158:159], v145, v[160:161]
	v_lshlrev_b64 v[160:161], v153, v[162:163]
	v_lshlrev_b64 v[162:163], v174, v[164:165]
	v_lshlrev_b64 v[164:165], v175, v[166:167]
	v_cvt_f32_u32_e32 v124, v124
	v_lshlrev_b64 v[154:155], v177, v[154:155]
	v_min_u32_e32 v156, 1, v156
	v_min_u32_e32 v158, 1, v158
	v_min_u32_e32 v160, 1, v160
	v_min_u32_e32 v162, 1, v162
	v_min_u32_e32 v164, 1, v164
	v_min_u32_e32 v154, 1, v154
	v_or_b32_e32 v125, v157, v156
	v_or_b32_e32 v156, v159, v158
	v_or_b32_e32 v157, v161, v160
	v_or_b32_e32 v158, v163, v162
	v_or_b32_e32 v159, v165, v164
	v_sub_u32_e32 v178, 32, v178
	v_or_b32_e32 v154, v155, v154
	v_cvt_f32_u32_e32 v155, v156
	v_cvt_f32_u32_e32 v156, v157
	v_cvt_f32_u32_e32 v157, v158
	v_cvt_f32_u32_e32 v158, v159
	v_ldexp_f32 v124, v124, v178
	v_mul_f32_e32 v124, 0x33800000, v124
	v_sub_u32_e32 v153, 32, v153
	v_sub_u32_e32 v175, 32, v175
	v_cvt_f32_u32_e32 v154, v154
	v_fmamk_f32 v124, v124, 0x3a800000, v152
	v_ffbh_u32_e32 v176, v169
	v_ldexp_f32 v153, v156, v153
	v_ldexp_f32 v156, v158, v175
	v_rsq_f32_e32 v158, v124
	v_min_u32_e32 v176, 32, v176
	v_sub_u32_e32 v145, 32, v145
	v_sub_u32_e32 v174, 32, v174
	v_lshlrev_b64 v[166:167], v176, v[168:169]
	v_sub_u32_e32 v169, 32, v177
	v_ldexp_f32 v145, v155, v145
	v_ldexp_f32 v155, v157, v174
	v_ldexp_f32 v154, v154, v169
	v_mul_f32_e32 v155, 0x33800000, v155
	v_mul_f32_e32 v124, 0x33800000, v154
	v_mul_f32_e32 v154, 0xbfb8aa3b, v158
	v_pk_mul_f32 v[122:123], v[122:123], v[154:155] op_sel_hi:[1,0]
	v_min_u32_e32 v166, 1, v166
	v_exp_f32_e32 v122, v122
	v_exp_f32_e32 v123, v123
	v_or_b32_e32 v160, v167, v166
	v_pk_mul_f32 v[120:121], v[120:121], v[154:155] op_sel_hi:[1,0]
	v_cvt_f32_u32_e32 v125, v125
	v_cvt_f32_u32_e32 v159, v160
	v_exp_f32_e32 v120, v120
	v_exp_f32_e32 v121, v121
	v_pk_add_f32 v[122:123], v[122:123], 1.0 op_sel_hi:[1,0]
	v_sub_u32_e32 v179, 32, v179
	v_rcp_f32_e32 v122, v122
	v_rcp_f32_e32 v123, v123
	v_sub_u32_e32 v168, 32, v176
	v_ldexp_f32 v125, v125, v179
	v_ldexp_f32 v157, v159, v168
	v_pk_add_f32 v[120:121], v[120:121], 1.0 op_sel_hi:[1,0]
	v_mul_f32_e32 v159, 0x33800000, v125
	v_mul_f32_e32 v160, 0x33800000, v156
	v_mul_f32_e32 v125, 0x33800000, v157
	v_pk_mul_f32 v[156:157], v[116:117], v[154:155] op_sel_hi:[1,0]
	v_rcp_f32_e32 v120, v120
	v_rcp_f32_e32 v121, v121
	v_mul_f32_e32 v158, v158, v158
	v_exp_f32_e32 v156, v156
	v_exp_f32_e32 v157, v157
	v_pk_mul_f32 v[122:123], v[158:159], v[122:123] op_sel_hi:[0,1]
	v_pk_mul_f32 v[122:123], v[126:127], v[122:123]
	v_pk_mul_f32 v[126:127], v[118:119], v[154:155] op_sel_hi:[1,0]
; __device__ __forceinline__ unsigned cvt_pk_bf16(float lo, float hi) { unsigned r; asm volatile("v_cvt_pk_bf16_f32 %0, %1, %2" : "=v"(r) : "v"(lo), "v"(hi)); return r; }
; __device__ __forceinline__ float ld_agent(const rss_t* p) { return (float)__hip_atomic_load(p, __ATOMIC_RELAXED, __HIP_MEMORY_SCOPE_AGENT) * (1.0f / 16777216.0f); }
; __device__ __forceinline__ unsigned silu_pk(f32x2 g, f32x2 u, float k1, float k2) {
;     const f32x2 t = g * k1; f32x2 ex; ex.x = __builtin_amdgcn_exp2f(t.x); ex.y = __builtin_amdgcn_exp2f(t.y);
;     const f32x2 d = ex + 1.0f; f32x2 r; r.x = __builtin_amdgcn_rcpf(d.x); r.y = __builtin_amdgcn_rcpf(d.y);
;     const f32x2 o = (g * u) * (r * k2);
;     return cvt_pk_bf16(o.x, o.y);
; }
; __device__ __forceinline__ float silu_mul(float g, float u) { return g * __builtin_amdgcn_rcpf(1.0f + __builtin_amdgcn_exp2f(-1.4426950408889634f * g)) * u; }
;     __device__ __forceinline__ void operator()(const f32x4 (&acc)[2][2][4][2], const Unit& u, int wr, int wc, int fr, int fq) const {
;         const int row0 = u.pm * BM + wr * 64 + fr, col0 = u.pn * HALF + wc * 32 + 8 * fq;
;         float ssq[2][4];
; #pragma unroll
;         for (int ai = 0; ai < 2; ++ai)
; #pragma unroll
;             for (int m = 0; m < 4; ++m) ssq[ai][m] = ld_agent(rowss + row0 + ai * HALF + m * 16);
; #pragma unroll
;         for (int ai = 0; ai < 2; ++ai)
; #pragma unroll
;             for (int m = 0; m < 4; ++m) {
;                 const int row = row0 + ai * HALF + m * 16; const float rs = __builtin_amdgcn_rsqf(ssq[ai][m] * (1.0f / 1024.0f) + 1e-6f);
;                 const float k1 = -1.4426950408889634f * rs, k2 = rs * rs;
;                 u32x4 w;
; #pragma unroll
;                 for (int n = 0; n < 2; ++n) {
;                     const f32x4 gv = acc[ai][0][m][n], uv = acc[ai][1][m][n];
;                     const unsigned lo = silu_pk((f32x2){gv[0], gv[1]}, (f32x2){uv[0], uv[1]}, k1, k2), hi = silu_pk((f32x2){gv[2], gv[3]}, (f32x2){uv[2], uv[3]}, k1, k2);
;                     if (n == 0) { w.x = lo; w.y = hi; } else { w.z = lo; w.w = hi; }
;                 }
;                 *(u32x4*)(O + (size_t)row * ldc + col0) = w;
	v_pk_mul_f32 v[120:121], v[158:159], v[120:121] op_sel_hi:[0,1]
	v_exp_f32_e32 v126, v126
	v_exp_f32_e32 v127, v127
	v_pk_add_f32 v[156:157], v[156:157], 1.0 op_sel_hi:[1,0]
	v_pk_mul_f32 v[120:121], v[172:173], v[120:121]
	v_mul_f32_e32 v145, 0x33800000, v145
	v_cvt_pk_bf16_f32 v120, v120, v121
	v_cvt_pk_bf16_f32 v121, v122, v123
	v_rcp_f32_e32 v122, v156
	v_rcp_f32_e32 v123, v157
	v_pk_add_f32 v[116:117], v[126:127], 1.0 op_sel_hi:[1,0]
	v_mul_f32_e32 v153, 0x33800000, v153
	v_rcp_f32_e32 v116, v116
	v_rcp_f32_e32 v117, v117
	v_pk_mul_f32 v[118:119], v[158:159], v[122:123] op_sel_hi:[0,1]
	v_pk_mul_f32 v[112:113], v[112:113], v[118:119]
	s_nop 0
	v_cvt_pk_bf16_f32 v122, v112, v113
	v_pk_mul_f32 v[112:113], v[158:159], v[116:117] op_sel_hi:[0,1]
	v_pk_mul_f32 v[112:113], v[114:115], v[112:113]
	v_fmamk_f32 v114, v159, 0x3a800000, v152
	v_rsq_f32_e32 v119, v114
	v_cvt_pk_bf16_f32 v123, v112, v113
	v_mov_b64_e32 v[112:113], s[12:13]
	v_mad_i64_i32 v[116:117], s[38:39], v144, s59, v[112:113]
	v_mul_f32_e32 v118, 0xbfb8aa3b, v119
	v_pk_mul_f32 v[126:127], v[108:109], v[118:119] op_sel_hi:[1,0]
	v_pk_mul_f32 v[108:109], v[110:111], v[118:119] op_sel_hi:[1,0]
	v_exp_f32_e32 v126, v126
	v_exp_f32_e32 v127, v127
	v_lshlrev_b64 v[114:115], 1, v[170:171]
	v_exp_f32_e32 v108, v108
	v_exp_f32_e32 v109, v109
	v_lshl_add_u64 v[116:117], v[116:117], 0, v[114:115]
	global_store_dwordx4 v[116:117], v[120:123], off
	v_mul_f32_e32 v116, v119, v119
	v_pk_add_f32 v[108:109], v[108:109], 1.0 op_sel_hi:[1,0]
	v_pk_add_f32 v[120:121], v[126:127], 1.0 op_sel_hi:[1,0]
	v_rcp_f32_e32 v108, v108
	v_rcp_f32_e32 v120, v120
	v_rcp_f32_e32 v121, v121
	v_rcp_f32_e32 v109, v109
	v_pk_mul_f32 v[110:111], v[116:117], v[120:121] op_sel_hi:[0,1]
	v_pk_mul_f32 v[104:105], v[104:105], v[110:111]
	v_pk_mul_f32 v[110:111], v[100:101], v[118:119] op_sel_hi:[1,0]
	v_pk_mul_f32 v[108:109], v[116:117], v[108:109] op_sel_hi:[0,1]
	v_exp_f32_e32 v110, v110
	v_exp_f32_e32 v111, v111
	v_pk_mul_f32 v[106:107], v[106:107], v[108:109]
	v_pk_mul_f32 v[108:109], v[102:103], v[118:119] op_sel_hi:[1,0]
	v_cvt_pk_bf16_f32 v104, v104, v105
	v_cvt_pk_bf16_f32 v105, v106, v107
	v_pk_add_f32 v[106:107], v[110:111], 1.0 op_sel_hi:[1,0]
	v_exp_f32_e32 v108, v108
	v_exp_f32_e32 v109, v109
	v_rcp_f32_e32 v106, v106
	v_rcp_f32_e32 v107, v107
	v_pk_add_f32 v[100:101], v[108:109], 1.0 op_sel_hi:[1,0]
	s_nop 0
	v_rcp_f32_e32 v100, v100
	v_rcp_f32_e32 v101, v101
	v_pk_mul_f32 v[102:103], v[116:117], v[106:107] op_sel_hi:[0,1]
	v_pk_mul_f32 v[96:97], v[96:97], v[102:103]
	s_nop 0
	v_cvt_pk_bf16_f32 v106, v96, v97
	v_pk_mul_f32 v[96:97], v[116:117], v[100:101] op_sel_hi:[0,1]
	v_pk_mul_f32 v[96:97], v[98:99], v[96:97]
	s_nop 0
	v_cvt_pk_bf16_f32 v107, v96, v97
	v_fmamk_f32 v96, v145, 0x3a800000, v152
	v_rsq_f32_e32 v99, v96
	v_or_b32_e32 v96, 16, v144
	v_mad_i64_i32 v[96:97], s[38:39], v96, s59, v[112:113]
	v_mul_f32_e32 v98, 0xbfb8aa3b, v99
	v_pk_mul_f32 v[100:101], v[92:93], v[98:99] op_sel_hi:[1,0]
	v_pk_mul_f32 v[92:93], v[94:95], v[98:99] op_sel_hi:[1,0]
	v_exp_f32_e32 v100, v100
	v_exp_f32_e32 v101, v101
	v_exp_f32_e32 v92, v92
	v_exp_f32_e32 v93, v93
	v_lshl_add_u64 v[96:97], v[96:97], 0, v[114:115]
	v_pk_add_f32 v[100:101], v[100:101], 1.0 op_sel_hi:[1,0]
	global_store_dwordx4 v[96:97], v[104:107], off
	v_rcp_f32_e32 v100, v100
	v_rcp_f32_e32 v101, v101
	v_pk_add_f32 v[92:93], v[92:93], 1.0 op_sel_hi:[1,0]
	v_mul_f32_e32 v96, v99, v99
	v_rcp_f32_e32 v92, v92
	v_rcp_f32_e32 v93, v93
	v_pk_mul_f32 v[94:95], v[96:97], v[100:101] op_sel_hi:[0,1]
	v_pk_mul_f32 v[88:89], v[88:89], v[94:95]
	v_pk_mul_f32 v[94:95], v[84:85], v[98:99] op_sel_hi:[1,0]
	v_pk_mul_f32 v[92:93], v[96:97], v[92:93] op_sel_hi:[0,1]
	v_exp_f32_e32 v94, v94
	v_exp_f32_e32 v95, v95
	v_pk_mul_f32 v[90:91], v[90:91], v[92:93]
	v_pk_mul_f32 v[92:93], v[86:87], v[98:99] op_sel_hi:[1,0]
	v_cvt_pk_bf16_f32 v88, v88, v89
	v_cvt_pk_bf16_f32 v89, v90, v91
	v_pk_add_f32 v[90:91], v[94:95], 1.0 op_sel_hi:[1,0]
	v_exp_f32_e32 v92, v92
	v_exp_f32_e32 v93, v93
	v_rcp_f32_e32 v90, v90
	v_rcp_f32_e32 v91, v91
	v_pk_add_f32 v[84:85], v[92:93], 1.0 op_sel_hi:[1,0]
	s_nop 0
	v_rcp_f32_e32 v84, v84
	v_rcp_f32_e32 v85, v85
	v_pk_mul_f32 v[86:87], v[96:97], v[90:91] op_sel_hi:[0,1]
	v_pk_mul_f32 v[80:81], v[80:81], v[86:87]
	s_nop 0
	v_cvt_pk_bf16_f32 v90, v80, v81
	v_pk_mul_f32 v[80:81], v[96:97], v[84:85] op_sel_hi:[0,1]
	v_pk_mul_f32 v[80:81], v[82:83], v[80:81]
	s_nop 0
	v_cvt_pk_bf16_f32 v91, v80, v81
	v_fmamk_f32 v80, v153, 0x3a800000, v152
	v_rsq_f32_e32 v83, v80
	v_or_b32_e32 v80, 32, v144
	v_mad_i64_i32 v[80:81], s[38:39], v80, s59, v[112:113]
	v_mul_f32_e32 v82, 0xbfb8aa3b, v83
	v_pk_mul_f32 v[84:85], v[76:77], v[82:83] op_sel_hi:[1,0]
	v_pk_mul_f32 v[76:77], v[78:79], v[82:83] op_sel_hi:[1,0]
	v_exp_f32_e32 v84, v84
	v_exp_f32_e32 v85, v85
	v_exp_f32_e32 v76, v76
	v_exp_f32_e32 v77, v77
	v_lshl_add_u64 v[80:81], v[80:81], 0, v[114:115]
	v_pk_add_f32 v[84:85], v[84:85], 1.0 op_sel_hi:[1,0]
	global_store_dwordx4 v[80:81], v[88:91], off
	v_rcp_f32_e32 v84, v84
	v_rcp_f32_e32 v85, v85
	v_pk_add_f32 v[76:77], v[76:77], 1.0 op_sel_hi:[1,0]
	v_mul_f32_e32 v80, v83, v83
	v_rcp_f32_e32 v76, v76
	v_rcp_f32_e32 v77, v77
	v_pk_mul_f32 v[78:79], v[80:81], v[84:85] op_sel_hi:[0,1]
	v_pk_mul_f32 v[72:73], v[72:73], v[78:79]
	v_pk_mul_f32 v[78:79], v[68:69], v[82:83] op_sel_hi:[1,0]
	v_pk_mul_f32 v[76:77], v[80:81], v[76:77] op_sel_hi:[0,1]
	v_exp_f32_e32 v78, v78
	v_exp_f32_e32 v79, v79
	v_pk_mul_f32 v[74:75], v[74:75], v[76:77]
	v_pk_mul_f32 v[76:77], v[70:71], v[82:83] op_sel_hi:[1,0]
	v_cvt_pk_bf16_f32 v72, v72, v73
	v_cvt_pk_bf16_f32 v73, v74, v75
; __device__ __forceinline__ unsigned cvt_pk_bf16(float lo, float hi) { unsigned r; asm volatile("v_cvt_pk_bf16_f32 %0, %1, %2" : "=v"(r) : "v"(lo), "v"(hi)); return r; }
; __device__ __forceinline__ float ld_agent(const rss_t* p) { return (float)__hip_atomic_load(p, __ATOMIC_RELAXED, __HIP_MEMORY_SCOPE_AGENT) * (1.0f / 16777216.0f); }
; __device__ __forceinline__ unsigned silu_pk(f32x2 g, f32x2 u, float k1, float k2) {
;     const f32x2 t = g * k1; f32x2 ex; ex.x = __builtin_amdgcn_exp2f(t.x); ex.y = __builtin_amdgcn_exp2f(t.y);
;     const f32x2 d = ex + 1.0f; f32x2 r; r.x = __builtin_amdgcn_rcpf(d.x); r.y = __builtin_amdgcn_rcpf(d.y);
;     const f32x2 o = (g * u) * (r * k2);
;     return cvt_pk_bf16(o.x, o.y);
; }
; __device__ __forceinline__ float silu_mul(float g, float u) { return g * __builtin_amdgcn_rcpf(1.0f + __builtin_amdgcn_exp2f(-1.4426950408889634f * g)) * u; }
;     __device__ __forceinline__ void operator()(const f32x4 (&acc)[2][2][4][2], const Unit& u, int wr, int wc, int fr, int fq) const {
;         const int row0 = u.pm * BM + wr * 64 + fr, col0 = u.pn * HALF + wc * 32 + 8 * fq;
;         float ssq[2][4];
; #pragma unroll
;         for (int ai = 0; ai < 2; ++ai)
; #pragma unroll
;             for (int m = 0; m < 4; ++m) ssq[ai][m] = ld_agent(rowss + row0 + ai * HALF + m * 16);
; #pragma unroll
;         for (int ai = 0; ai < 2; ++ai)
; #pragma unroll
;             for (int m = 0; m < 4; ++m) {
;                 const int row = row0 + ai * HALF + m * 16; const float rs = __builtin_amdgcn_rsqf(ssq[ai][m] * (1.0f / 1024.0f) + 1e-6f);
;                 const float k1 = -1.4426950408889634f * rs, k2 = rs * rs;
;                 u32x4 w;
; #pragma unroll
;                 for (int n = 0; n < 2; ++n) {
;                     const f32x4 gv = acc[ai][0][m][n], uv = acc[ai][1][m][n];
;                     const unsigned lo = silu_pk((f32x2){gv[0], gv[1]}, (f32x2){uv[0], uv[1]}, k1, k2), hi = silu_pk((f32x2){gv[2], gv[3]}, (f32x2){uv[2], uv[3]}, k1, k2);
;                     if (n == 0) { w.x = lo; w.y = hi; } else { w.z = lo; w.w = hi; }
;                 }
;                 *(u32x4*)(O + (size_t)row * ldc + col0) = w;
	v_pk_add_f32 v[74:75], v[78:79], 1.0 op_sel_hi:[1,0]
	v_exp_f32_e32 v76, v76
	v_exp_f32_e32 v77, v77
	v_rcp_f32_e32 v74, v74
	v_rcp_f32_e32 v75, v75
	v_pk_add_f32 v[68:69], v[76:77], 1.0 op_sel_hi:[1,0]
	s_nop 0
	v_rcp_f32_e32 v68, v68
	v_rcp_f32_e32 v69, v69
	v_pk_mul_f32 v[70:71], v[80:81], v[74:75] op_sel_hi:[0,1]
	v_pk_mul_f32 v[64:65], v[64:65], v[70:71]
	s_nop 0
	v_cvt_pk_bf16_f32 v74, v64, v65
	v_pk_mul_f32 v[64:65], v[80:81], v[68:69] op_sel_hi:[0,1]
	v_pk_mul_f32 v[64:65], v[66:67], v[64:65]
	s_nop 0
	v_cvt_pk_bf16_f32 v75, v64, v65
	v_fmamk_f32 v65, v155, 0x3a800000, v152
	v_rsq_f32_e32 v67, v65
	v_or_b32_e32 v64, 48, v144
	v_mad_i64_i32 v[64:65], s[38:39], v64, s59, v[112:113]
	v_mul_f32_e32 v66, 0xbfb8aa3b, v67
	v_pk_mul_f32 v[68:69], v[60:61], v[66:67] op_sel_hi:[1,0]
	v_pk_mul_f32 v[60:61], v[62:63], v[66:67] op_sel_hi:[1,0]
	v_exp_f32_e32 v68, v68
	v_exp_f32_e32 v69, v69
	v_exp_f32_e32 v60, v60
	v_exp_f32_e32 v61, v61
	v_lshl_add_u64 v[64:65], v[64:65], 0, v[114:115]
	v_pk_add_f32 v[68:69], v[68:69], 1.0 op_sel_hi:[1,0]
	global_store_dwordx4 v[64:65], v[72:75], off
	v_rcp_f32_e32 v68, v68
	v_rcp_f32_e32 v69, v69
	v_pk_add_f32 v[60:61], v[60:61], 1.0 op_sel_hi:[1,0]
	v_add_u32_e32 v65, 0x80, v144
	v_rcp_f32_e32 v60, v60
	v_rcp_f32_e32 v61, v61
	v_mul_f32_e32 v64, v67, v67
	v_pk_mul_f32 v[62:63], v[64:65], v[68:69] op_sel_hi:[0,1]
	v_pk_mul_f32 v[56:57], v[56:57], v[62:63]
	v_pk_mul_f32 v[62:63], v[52:53], v[66:67] op_sel_hi:[1,0]
	v_pk_mul_f32 v[60:61], v[64:65], v[60:61] op_sel_hi:[0,1]
	v_exp_f32_e32 v62, v62
	v_exp_f32_e32 v63, v63
	v_pk_mul_f32 v[58:59], v[58:59], v[60:61]
	v_pk_mul_f32 v[60:61], v[54:55], v[66:67] op_sel_hi:[1,0]
	v_cvt_pk_bf16_f32 v56, v56, v57
	v_cvt_pk_bf16_f32 v57, v58, v59
	v_pk_add_f32 v[58:59], v[62:63], 1.0 op_sel_hi:[1,0]
	v_exp_f32_e32 v60, v60
	v_exp_f32_e32 v61, v61
	v_rcp_f32_e32 v58, v58
	v_rcp_f32_e32 v59, v59
	v_pk_add_f32 v[52:53], v[60:61], 1.0 op_sel_hi:[1,0]
	s_nop 0
	v_rcp_f32_e32 v52, v52
	v_rcp_f32_e32 v53, v53
	v_pk_mul_f32 v[54:55], v[64:65], v[58:59] op_sel_hi:[0,1]
	v_pk_mul_f32 v[48:49], v[48:49], v[54:55]
	s_nop 0
	v_cvt_pk_bf16_f32 v58, v48, v49
	v_pk_mul_f32 v[48:49], v[64:65], v[52:53] op_sel_hi:[0,1]
	v_pk_mul_f32 v[48:49], v[50:51], v[48:49]
	v_fmamk_f32 v50, v160, 0x3a800000, v152
	v_rsq_f32_e32 v51, v50
	v_cvt_pk_bf16_f32 v59, v48, v49
	v_mad_i64_i32 v[48:49], s[38:39], v65, s59, v[112:113]
	v_mul_f32_e32 v50, 0xbfb8aa3b, v51
	v_pk_mul_f32 v[52:53], v[44:45], v[50:51] op_sel_hi:[1,0]
	v_pk_mul_f32 v[44:45], v[46:47], v[50:51] op_sel_hi:[1,0]
	v_exp_f32_e32 v52, v52
	v_exp_f32_e32 v53, v53
	v_exp_f32_e32 v44, v44
	v_exp_f32_e32 v45, v45
	v_lshl_add_u64 v[48:49], v[48:49], 0, v[114:115]
	v_pk_add_f32 v[52:53], v[52:53], 1.0 op_sel_hi:[1,0]
	global_store_dwordx4 v[48:49], v[56:59], off
	v_rcp_f32_e32 v52, v52
	v_rcp_f32_e32 v53, v53
	v_pk_add_f32 v[44:45], v[44:45], 1.0 op_sel_hi:[1,0]
	v_mul_f32_e32 v48, v51, v51
	v_rcp_f32_e32 v44, v44
	v_rcp_f32_e32 v45, v45
	v_pk_mul_f32 v[46:47], v[48:49], v[52:53] op_sel_hi:[0,1]
	v_pk_mul_f32 v[40:41], v[40:41], v[46:47]
	v_pk_mul_f32 v[46:47], v[36:37], v[50:51] op_sel_hi:[1,0]
	v_pk_mul_f32 v[44:45], v[48:49], v[44:45] op_sel_hi:[0,1]
	v_exp_f32_e32 v46, v46
	v_exp_f32_e32 v47, v47
	v_pk_mul_f32 v[42:43], v[42:43], v[44:45]
	v_pk_mul_f32 v[44:45], v[38:39], v[50:51] op_sel_hi:[1,0]
	v_cvt_pk_bf16_f32 v40, v40, v41
	v_cvt_pk_bf16_f32 v41, v42, v43
	v_pk_add_f32 v[42:43], v[46:47], 1.0 op_sel_hi:[1,0]
	v_exp_f32_e32 v44, v44
	v_exp_f32_e32 v45, v45
	v_rcp_f32_e32 v42, v42
	v_rcp_f32_e32 v43, v43
	v_pk_add_f32 v[36:37], v[44:45], 1.0 op_sel_hi:[1,0]
	s_nop 0
	v_rcp_f32_e32 v36, v36
	v_rcp_f32_e32 v37, v37
	v_pk_mul_f32 v[38:39], v[48:49], v[42:43] op_sel_hi:[0,1]
	v_pk_mul_f32 v[32:33], v[32:33], v[38:39]
	s_nop 0
	v_cvt_pk_bf16_f32 v42, v32, v33
; __device__ __forceinline__ unsigned cvt_pk_bf16(float lo, float hi) { unsigned r; asm volatile("v_cvt_pk_bf16_f32 %0, %1, %2" : "=v"(r) : "v"(lo), "v"(hi)); return r; }
; __device__ __forceinline__ unsigned silu_pk(f32x2 g, f32x2 u, float k1, float k2) {
;     const f32x2 t = g * k1; f32x2 ex; ex.x = __builtin_amdgcn_exp2f(t.x); ex.y = __builtin_amdgcn_exp2f(t.y);
;     const f32x2 d = ex + 1.0f; f32x2 r; r.x = __builtin_amdgcn_rcpf(d.x); r.y = __builtin_amdgcn_rcpf(d.y);
;     const f32x2 o = (g * u) * (r * k2);
;     return cvt_pk_bf16(o.x, o.y);
; }
; __device__ __forceinline__ float silu_mul(float g, float u) { return g * __builtin_amdgcn_rcpf(1.0f + __builtin_amdgcn_exp2f(-1.4426950408889634f * g)) * u; }
;     __device__ __forceinline__ void operator()(const f32x4 (&acc)[2][2][4][2], const Unit& u, int wr, int wc, int fr, int fq) const {
;         const int row0 = u.pm * BM + wr * 64 + fr, col0 = u.pn * HALF + wc * 32 + 8 * fq;
;         float ssq[2][4];
; #pragma unroll
;         for (int ai = 0; ai < 2; ++ai)
; #pragma unroll
;             for (int m = 0; m < 4; ++m) ssq[ai][m] = ld_agent(rowss + row0 + ai * HALF + m * 16);
; #pragma unroll
;         for (int ai = 0; ai < 2; ++ai)
; #pragma unroll
;             for (int m = 0; m < 4; ++m) {
;                 const int row = row0 + ai * HALF + m * 16; const float rs = __builtin_amdgcn_rsqf(ssq[ai][m] * (1.0f / 1024.0f) + 1e-6f);
;                 const float k1 = -1.4426950408889634f * rs, k2 = rs * rs;
;                 u32x4 w;
; #pragma unroll
;                 for (int n = 0; n < 2; ++n) {
;                     const f32x4 gv = acc[ai][0][m][n], uv = acc[ai][1][m][n];
;                     const unsigned lo = silu_pk((f32x2){gv[0], gv[1]}, (f32x2){uv[0], uv[1]}, k1, k2), hi = silu_pk((f32x2){gv[2], gv[3]}, (f32x2){uv[2], uv[3]}, k1, k2);
;                     if (n == 0) { w.x = lo; w.y = hi; } else { w.z = lo; w.w = hi; }
;                 }
;                 *(u32x4*)(O + (size_t)row * ldc + col0) = w;
; template <class Epi, class Sched, bool ALIGN_EPI = false, bool SP2 = false>
; __device__ __forceinline__ void gemm_phase(PG8_LAS unsigned char* lds, const Gemm g, const Sched& S, const Epi& E) {
;     ...
;         if constexpr (!Epi::AFTER_DRAIN) { E(acc, cur, wr, wc, fr, fq); S.done(cur); }
;         if (!has_next) break;
; #pragma unroll
	v_pk_mul_f32 v[32:33], v[48:49], v[36:37] op_sel_hi:[0,1]
	v_pk_mul_f32 v[32:33], v[34:35], v[32:33]
	s_nop 0
	v_cvt_pk_bf16_f32 v43, v32, v33
	v_fmamk_f32 v32, v125, 0x3a800000, v152
	v_rsq_f32_e32 v35, v32
	v_add_u32_e32 v32, 0x90, v144
	v_mad_i64_i32 v[32:33], s[38:39], v32, s59, v[112:113]
	v_mul_f32_e32 v34, 0xbfb8aa3b, v35
	v_pk_mul_f32 v[36:37], v[28:29], v[34:35] op_sel_hi:[1,0]
	v_pk_mul_f32 v[28:29], v[30:31], v[34:35] op_sel_hi:[1,0]
	v_exp_f32_e32 v36, v36
	v_exp_f32_e32 v37, v37
	v_exp_f32_e32 v28, v28
	v_exp_f32_e32 v29, v29
	v_lshl_add_u64 v[32:33], v[32:33], 0, v[114:115]
	v_pk_add_f32 v[36:37], v[36:37], 1.0 op_sel_hi:[1,0]
	global_store_dwordx4 v[32:33], v[40:43], off
	v_rcp_f32_e32 v36, v36
	v_rcp_f32_e32 v37, v37
	v_pk_add_f32 v[28:29], v[28:29], 1.0 op_sel_hi:[1,0]
	v_mul_f32_e32 v32, v35, v35
	v_rcp_f32_e32 v28, v28
	v_rcp_f32_e32 v29, v29
	v_pk_mul_f32 v[30:31], v[32:33], v[36:37] op_sel_hi:[0,1]
	v_pk_mul_f32 v[24:25], v[24:25], v[30:31]
	v_pk_mul_f32 v[30:31], v[20:21], v[34:35] op_sel_hi:[1,0]
	v_pk_mul_f32 v[28:29], v[32:33], v[28:29] op_sel_hi:[0,1]
	v_exp_f32_e32 v30, v30
	v_exp_f32_e32 v31, v31
	v_pk_mul_f32 v[26:27], v[26:27], v[28:29]
	v_pk_mul_f32 v[28:29], v[22:23], v[34:35] op_sel_hi:[1,0]
	v_cvt_pk_bf16_f32 v24, v24, v25
	v_cvt_pk_bf16_f32 v25, v26, v27
	v_pk_add_f32 v[26:27], v[30:31], 1.0 op_sel_hi:[1,0]
	v_exp_f32_e32 v28, v28
	v_exp_f32_e32 v29, v29
	v_rcp_f32_e32 v26, v26
	v_rcp_f32_e32 v27, v27
	v_pk_add_f32 v[20:21], v[28:29], 1.0 op_sel_hi:[1,0]
	s_nop 0
	v_rcp_f32_e32 v20, v20
	v_rcp_f32_e32 v21, v21
	v_pk_mul_f32 v[22:23], v[32:33], v[26:27] op_sel_hi:[0,1]
	v_pk_mul_f32 v[16:17], v[16:17], v[22:23]
	s_nop 0
	v_cvt_pk_bf16_f32 v26, v16, v17
	v_pk_mul_f32 v[16:17], v[32:33], v[20:21] op_sel_hi:[0,1]
	v_pk_mul_f32 v[16:17], v[18:19], v[16:17]
	s_nop 0
	v_cvt_pk_bf16_f32 v27, v16, v17
	v_fmamk_f32 v16, v124, 0x3a800000, v152
	v_rsq_f32_e32 v19, v16
	v_add_u32_e32 v16, 0xa0, v144
	v_mad_i64_i32 v[16:17], s[38:39], v16, s59, v[112:113]
	v_mul_f32_e32 v18, 0xbfb8aa3b, v19
	v_pk_mul_f32 v[20:21], v[12:13], v[18:19] op_sel_hi:[1,0]
	v_pk_mul_f32 v[12:13], v[14:15], v[18:19] op_sel_hi:[1,0]
	v_exp_f32_e32 v20, v20
	v_exp_f32_e32 v21, v21
	v_exp_f32_e32 v12, v12
	v_exp_f32_e32 v13, v13
	v_lshl_add_u64 v[16:17], v[16:17], 0, v[114:115]
	v_pk_add_f32 v[20:21], v[20:21], 1.0 op_sel_hi:[1,0]
	global_store_dwordx4 v[16:17], v[24:27], off
	v_rcp_f32_e32 v20, v20
	v_rcp_f32_e32 v21, v21
	v_pk_add_f32 v[12:13], v[12:13], 1.0 op_sel_hi:[1,0]
	v_mul_f32_e32 v16, v19, v19
	v_rcp_f32_e32 v12, v12
	v_rcp_f32_e32 v13, v13
	v_pk_mul_f32 v[14:15], v[16:17], v[20:21] op_sel_hi:[0,1]
	v_pk_mul_f32 v[8:9], v[8:9], v[14:15]
	v_pk_mul_f32 v[14:15], v[4:5], v[18:19] op_sel_hi:[1,0]
	v_pk_mul_f32 v[12:13], v[16:17], v[12:13] op_sel_hi:[0,1]
	v_exp_f32_e32 v14, v14
	v_exp_f32_e32 v15, v15
	v_pk_mul_f32 v[10:11], v[10:11], v[12:13]
	v_pk_mul_f32 v[12:13], v[6:7], v[18:19] op_sel_hi:[1,0]
	v_cvt_pk_bf16_f32 v8, v8, v9
	v_cvt_pk_bf16_f32 v9, v10, v11
	v_pk_add_f32 v[10:11], v[14:15], 1.0 op_sel_hi:[1,0]
	v_exp_f32_e32 v12, v12
	v_exp_f32_e32 v13, v13
	v_rcp_f32_e32 v10, v10
	v_rcp_f32_e32 v11, v11
	v_pk_add_f32 v[4:5], v[12:13], 1.0 op_sel_hi:[1,0]
	s_nop 0
	v_rcp_f32_e32 v4, v4
	v_rcp_f32_e32 v5, v5
	v_pk_mul_f32 v[6:7], v[16:17], v[10:11] op_sel_hi:[0,1]
	v_pk_mul_f32 v[0:1], v[0:1], v[6:7]
	s_nop 0
	v_cvt_pk_bf16_f32 v10, v0, v1
	v_pk_mul_f32 v[0:1], v[16:17], v[4:5] op_sel_hi:[0,1]
	v_pk_mul_f32 v[0:1], v[2:3], v[0:1]
	s_nop 0
	v_cvt_pk_bf16_f32 v11, v0, v1
	v_add_u32_e32 v0, 0xb0, v144
	v_mad_i64_i32 v[0:1], s[38:39], v0, s59, v[112:113]
	v_lshl_add_u64 v[0:1], v[0:1], 0, v[114:115]
	global_store_dwordx4 v[0:1], v[8:11], off
	s_cbranch_vccnz .LBB0_228
	s_andn2_b64 vcc, exec, s[6:7]
	s_cbranch_vccnz .LBB0_227
	s_barrier
	s_branch .LBB0_227

; __device__ __forceinline__ unsigned cvt_pk_bf16(float lo, float hi) { unsigned r; asm volatile("v_cvt_pk_bf16_f32 %0, %1, %2" : "=v"(r) : "v"(lo), "v"(hi)); return r; }
; #define PG8_SCHED __builtin_amdgcn_sched_barrier(0)
; __device__ __forceinline__ float ld_agent(const rss_t* p) { return (float)__hip_atomic_load(p, __ATOMIC_RELAXED, __HIP_MEMORY_SCOPE_AGENT) * (1.0f / 16777216.0f); }
; __device__ __forceinline__ rss_t rss_fix(float ss) { return (rss_t)(ss * 16777216.0f); }
; __device__ __forceinline__ float rstd_of(const rss_t* rowss, int row) { return __builtin_amdgcn_rsqf(ld_agent(rowss + row) * (1.0f / 1024.0f) + 1e-6f); }
; __device__ __forceinline__ unsigned silu_pk(f32x2 g, f32x2 u, float k1, float k2) {
;     const f32x2 t = g * k1; f32x2 ex; ex.x = __builtin_amdgcn_exp2f(t.x); ex.y = __builtin_amdgcn_exp2f(t.y);
;     const f32x2 d = ex + 1.0f; f32x2 r; r.x = __builtin_amdgcn_rcpf(d.x); r.y = __builtin_amdgcn_rcpf(d.y);
;     const f32x2 o = (g * u) * (r * k2);
;     return cvt_pk_bf16(o.x, o.y);
; }
; __device__ __forceinline__ float silu_mul(float g, float u) { return g * __builtin_amdgcn_rcpf(1.0f + __builtin_amdgcn_exp2f(-1.4426950408889634f * g)) * u; }
;     __device__ __forceinline__ void operator()(const f32x4 (&acc)[2][2][4][2], const Unit& u, int wr, int wc, int fr, int fq) const {
;         const int row0 = u.pm * BM + wr * 64 + fr, col0 = u.pn * HALF + wc * 32 + 8 * fq;
;         float ssq[2][4];
; #pragma unroll
;         for (int ai = 0; ai < 2; ++ai)
; #pragma unroll
;             for (int m = 0; m < 4; ++m) ssq[ai][m] = ld_agent(rowss + row0 + ai * HALF + m * 16);
; #pragma unroll
;         for (int ai = 0; ai < 2; ++ai)
; #pragma unroll
;             for (int m = 0; m < 4; ++m) {
;                 const int row = row0 + ai * HALF + m * 16; const float rs = __builtin_amdgcn_rsqf(ssq[ai][m] * (1.0f / 1024.0f) + 1e-6f);
;                 const float k1 = -1.4426950408889634f * rs, k2 = rs * rs;
; template <class Epi, class Sched, bool ALIGN_EPI = false, bool SP2 = false>
; __device__ __forceinline__ void gemm_phase(PG8_LAS unsigned char* lds, const Gemm g, const Sched& S, const Epi& E) {
;     ...
;             PG8_LDB(B0, 0, 0); PG8_LDB(B1, 0, 1); PG8_SCHED; PG8_LDA(At, 0, 0); PG8_STAGE(PG8_SA(1, 1), a1 + hstep, voffA);
.LBB0_1197:
	v_lshl_add_u32 v144, s36, 8, v146
	v_ashrrev_i32_e32 v145, 31, v144
	v_lshl_add_u64 v[154:155], v[144:145], 3, s[12:13]
	global_load_dwordx2 v[156:157], v[154:155], off sc1
	global_load_dwordx2 v[158:159], v[154:155], off offset:128 sc1
	global_load_dwordx2 v[160:161], v[154:155], off offset:256 sc1
	global_load_dwordx2 v[162:163], v[154:155], off offset:384 sc1
	global_load_dwordx2 v[164:165], v[154:155], off offset:1024 sc1
	global_load_dwordx2 v[166:167], v[154:155], off offset:1152 sc1
	global_load_dwordx2 v[168:169], v[154:155], off offset:1280 sc1
	s_nop 0
	global_load_dwordx2 v[154:155], v[154:155], off offset:1408 sc1
	v_pk_mul_f32 v[172:173], v[120:121], v[124:125]
	v_pk_mul_f32 v[126:127], v[122:123], v[126:127]
	v_pk_mul_f32 v[112:113], v[116:117], v[112:113]
	v_pk_mul_f32 v[114:115], v[118:119], v[114:115]
	v_lshl_or_b32 v170, s63, 7, v148
	v_ashrrev_i32_e32 v171, 31, v170
	v_pk_mul_f32 v[104:105], v[108:109], v[104:105]
	v_pk_mul_f32 v[106:107], v[110:111], v[106:107]
	v_pk_mul_f32 v[96:97], v[100:101], v[96:97]
	v_pk_mul_f32 v[98:99], v[102:103], v[98:99]
	v_pk_mul_f32 v[88:89], v[92:93], v[88:89]
	v_pk_mul_f32 v[90:91], v[94:95], v[90:91]
	v_pk_mul_f32 v[80:81], v[84:85], v[80:81]
	v_pk_mul_f32 v[82:83], v[86:87], v[82:83]
	v_pk_mul_f32 v[72:73], v[76:77], v[72:73]
	v_pk_mul_f32 v[74:75], v[78:79], v[74:75]
	v_pk_mul_f32 v[64:65], v[68:69], v[64:65]
	v_pk_mul_f32 v[66:67], v[70:71], v[66:67]
	v_pk_mul_f32 v[56:57], v[60:61], v[56:57]
	v_pk_mul_f32 v[58:59], v[62:63], v[58:59]
	v_pk_mul_f32 v[48:49], v[52:53], v[48:49]
	v_pk_mul_f32 v[50:51], v[54:55], v[50:51]
	v_pk_mul_f32 v[40:41], v[44:45], v[40:41]
	v_pk_mul_f32 v[42:43], v[46:47], v[42:43]
	v_pk_mul_f32 v[32:33], v[36:37], v[32:33]
	v_pk_mul_f32 v[34:35], v[38:39], v[34:35]
	v_pk_mul_f32 v[24:25], v[28:29], v[24:25]
	v_pk_mul_f32 v[26:27], v[30:31], v[26:27]
	v_pk_mul_f32 v[16:17], v[20:21], v[16:17]
	v_pk_mul_f32 v[18:19], v[22:23], v[18:19]
	v_pk_mul_f32 v[8:9], v[12:13], v[8:9]
	v_pk_mul_f32 v[10:11], v[14:15], v[10:11]
	v_pk_mul_f32 v[0:1], v[4:5], v[0:1]
	v_pk_mul_f32 v[2:3], v[6:7], v[2:3]
	s_andn2_b64 vcc, exec, s[4:5]
	s_mov_b64 s[4:5], -1
	s_waitcnt vmcnt(0)
	s_cbranch_vccnz .Lhoist_skip_1
	s_add_u32 s96, s22, 0x40080
	s_addc_u32 s97, s23, 0
	v_lshl_add_u64 v[224:225], s[96:97], 0, v[136:137]
	s_add_i32 m0, s37, 0xc000
	s_nop 0
	global_load_lds_dwordx4 v[224:225], off
	v_lshl_add_u64 v[224:225], s[96:97], 0, v[138:139]
	s_add_i32 m0, s37, 0xe000
	s_nop 0
	global_load_lds_dwordx4 v[224:225], off
.Lhoist_skip_1:
	v_ffbh_u32_e32 v124, v157
	v_ffbh_u32_e32 v125, v159
	v_min_u32_e32 v178, 32, v124
	v_min_u32_e32 v179, 32, v125
	v_lshlrev_b64 v[124:125], v178, v[156:157]
	v_ffbh_u32_e32 v145, v161
	v_ffbh_u32_e32 v153, v163
	v_ffbh_u32_e32 v174, v165
	v_ffbh_u32_e32 v175, v167
	v_min_u32_e32 v124, 1, v124
	v_ffbh_u32_e32 v177, v155
	v_min_u32_e32 v145, 32, v145
	v_min_u32_e32 v153, 32, v153
	v_min_u32_e32 v174, 32, v174
	v_min_u32_e32 v175, 32, v175
	v_or_b32_e32 v124, v125, v124
	v_min_u32_e32 v177, 32, v177
	v_lshlrev_b64 v[156:157], v179, v[158:159]
	v_lshlrev_b64 v[158:159], v145, v[160:161]
	v_lshlrev_b64 v[160:161], v153, v[162:163]
	v_lshlrev_b64 v[162:163], v174, v[164:165]
	v_lshlrev_b64 v[164:165], v175, v[166:167]
	v_cvt_f32_u32_e32 v124, v124
	v_lshlrev_b64 v[154:155], v177, v[154:155]
	v_min_u32_e32 v156, 1, v156
	v_min_u32_e32 v158, 1, v158
	v_min_u32_e32 v160, 1, v160
	v_min_u32_e32 v162, 1, v162
	v_min_u32_e32 v164, 1, v164
	v_min_u32_e32 v154, 1, v154
	v_or_b32_e32 v125, v157, v156
	v_or_b32_e32 v156, v159, v158
	v_or_b32_e32 v157, v161, v160
	v_or_b32_e32 v158, v163, v162
	v_or_b32_e32 v159, v165, v164
	v_sub_u32_e32 v178, 32, v178
	v_or_b32_e32 v154, v155, v154
	v_cvt_f32_u32_e32 v155, v156
	v_cvt_f32_u32_e32 v156, v157
	v_cvt_f32_u32_e32 v157, v158
	v_cvt_f32_u32_e32 v158, v159
	v_ldexp_f32 v124, v124, v178
	v_mul_f32_e32 v124, 0x33800000, v124
	v_sub_u32_e32 v153, 32, v153
	v_sub_u32_e32 v175, 32, v175
	v_cvt_f32_u32_e32 v154, v154
	v_fmamk_f32 v124, v124, 0x3a800000, v152
	v_ffbh_u32_e32 v176, v169
	v_ldexp_f32 v153, v156, v153
	v_ldexp_f32 v156, v158, v175
	v_rsq_f32_e32 v158, v124
	v_min_u32_e32 v176, 32, v176
	v_sub_u32_e32 v145, 32, v145
	v_sub_u32_e32 v174, 32, v174
	v_lshlrev_b64 v[166:167], v176, v[168:169]
	v_sub_u32_e32 v169, 32, v177
	v_ldexp_f32 v145, v155, v145
	v_ldexp_f32 v155, v157, v174
	v_ldexp_f32 v154, v154, v169
	v_mul_f32_e32 v155, 0x33800000, v155
	v_mul_f32_e32 v124, 0x33800000, v154
	v_mul_f32_e32 v154, 0xbfb8aa3b, v158
	v_pk_mul_f32 v[122:123], v[122:123], v[154:155] op_sel_hi:[1,0]
	v_min_u32_e32 v166, 1, v166
	v_exp_f32_e32 v122, v122
	v_exp_f32_e32 v123, v123
	v_or_b32_e32 v160, v167, v166
	v_pk_mul_f32 v[120:121], v[120:121], v[154:155] op_sel_hi:[1,0]
	v_cvt_f32_u32_e32 v125, v125
	v_cvt_f32_u32_e32 v159, v160
	v_exp_f32_e32 v120, v120
	v_exp_f32_e32 v121, v121
	v_pk_add_f32 v[122:123], v[122:123], 1.0 op_sel_hi:[1,0]
	v_sub_u32_e32 v179, 32, v179
	v_rcp_f32_e32 v122, v122
	v_rcp_f32_e32 v123, v123
	v_sub_u32_e32 v168, 32, v176
	v_ldexp_f32 v125, v125, v179
	v_ldexp_f32 v157, v159, v168
	v_pk_add_f32 v[120:121], v[120:121], 1.0 op_sel_hi:[1,0]
	v_mul_f32_e32 v159, 0x33800000, v125
	v_mul_f32_e32 v160, 0x33800000, v156
	v_mul_f32_e32 v125, 0x33800000, v157
	v_pk_mul_f32 v[156:157], v[116:117], v[154:155] op_sel_hi:[1,0]
	v_rcp_f32_e32 v120, v120
	v_rcp_f32_e32 v121, v121
	v_mul_f32_e32 v158, v158, v158
	v_exp_f32_e32 v156, v156
	v_exp_f32_e32 v157, v157
	v_pk_mul_f32 v[122:123], v[158:159], v[122:123] op_sel_hi:[0,1]
	v_pk_mul_f32 v[122:123], v[126:127], v[122:123]
	v_pk_mul_f32 v[126:127], v[118:119], v[154:155] op_sel_hi:[1,0]
; __device__ __forceinline__ unsigned cvt_pk_bf16(float lo, float hi) { unsigned r; asm volatile("v_cvt_pk_bf16_f32 %0, %1, %2" : "=v"(r) : "v"(lo), "v"(hi)); return r; }
; __device__ __forceinline__ unsigned silu_pk(f32x2 g, f32x2 u, float k1, float k2) {
;     const f32x2 t = g * k1; f32x2 ex; ex.x = __builtin_amdgcn_exp2f(t.x); ex.y = __builtin_amdgcn_exp2f(t.y);
;     const f32x2 d = ex + 1.0f; f32x2 r; r.x = __builtin_amdgcn_rcpf(d.x); r.y = __builtin_amdgcn_rcpf(d.y);
;     const f32x2 o = (g * u) * (r * k2);
;     return cvt_pk_bf16(o.x, o.y);
;     __device__ __forceinline__ void operator()(const f32x4 (&acc)[2][2][4][2], const Unit& u, int wr, int wc, int fr, int fq) const {
;     ...
;             for (int m = 0; m < 4; ++m) {
;                 const int row = row0 + ai * HALF + m * 16; const float rs = __builtin_amdgcn_rsqf(ssq[ai][m] * (1.0f / 1024.0f) + 1e-6f);
;                 const float k1 = -1.4426950408889634f * rs, k2 = rs * rs;
;                 u32x4 w;
; #pragma unroll
;                 for (int n = 0; n < 2; ++n) {
;                     const f32x4 gv = acc[ai][0][m][n], uv = acc[ai][1][m][n];
;                     const unsigned lo = silu_pk((f32x2){gv[0], gv[1]}, (f32x2){uv[0], uv[1]}, k1, k2), hi = silu_pk((f32x2){gv[2], gv[3]}, (f32x2){uv[2], uv[3]}, k1, k2);
;                     if (n == 0) { w.x = lo; w.y = hi; } else { w.z = lo; w.w = hi; }
;                 }
;                 *(u32x4*)(O + (size_t)row * ldc + col0) = w;
	v_pk_mul_f32 v[120:121], v[158:159], v[120:121] op_sel_hi:[0,1]
	v_exp_f32_e32 v126, v126
	v_exp_f32_e32 v127, v127
	v_pk_add_f32 v[156:157], v[156:157], 1.0 op_sel_hi:[1,0]
	v_pk_mul_f32 v[120:121], v[172:173], v[120:121]
	v_mul_f32_e32 v145, 0x33800000, v145
	v_cvt_pk_bf16_f32 v120, v120, v121
	v_cvt_pk_bf16_f32 v121, v122, v123
	v_rcp_f32_e32 v122, v156
	v_rcp_f32_e32 v123, v157
	v_pk_add_f32 v[116:117], v[126:127], 1.0 op_sel_hi:[1,0]
	v_mul_f32_e32 v153, 0x33800000, v153
	v_rcp_f32_e32 v116, v116
	v_rcp_f32_e32 v117, v117
	v_pk_mul_f32 v[118:119], v[158:159], v[122:123] op_sel_hi:[0,1]
	v_pk_mul_f32 v[112:113], v[112:113], v[118:119]
	s_nop 0
	v_cvt_pk_bf16_f32 v122, v112, v113
	v_pk_mul_f32 v[112:113], v[158:159], v[116:117] op_sel_hi:[0,1]
	v_pk_mul_f32 v[112:113], v[114:115], v[112:113]
	v_fmamk_f32 v114, v159, 0x3a800000, v152
	v_rsq_f32_e32 v119, v114
	v_cvt_pk_bf16_f32 v123, v112, v113
	v_mov_b64_e32 v[112:113], s[8:9]
	v_mad_i64_i32 v[116:117], s[38:39], v144, s59, v[112:113]
	v_mul_f32_e32 v118, 0xbfb8aa3b, v119
	v_pk_mul_f32 v[126:127], v[108:109], v[118:119] op_sel_hi:[1,0]
	v_pk_mul_f32 v[108:109], v[110:111], v[118:119] op_sel_hi:[1,0]
	v_exp_f32_e32 v126, v126
	v_exp_f32_e32 v127, v127
	v_lshlrev_b64 v[114:115], 1, v[170:171]
	v_exp_f32_e32 v108, v108
	v_exp_f32_e32 v109, v109
	v_lshl_add_u64 v[116:117], v[116:117], 0, v[114:115]
	global_store_dwordx4 v[116:117], v[120:123], off
	v_mul_f32_e32 v116, v119, v119
	v_pk_add_f32 v[108:109], v[108:109], 1.0 op_sel_hi:[1,0]
	v_pk_add_f32 v[120:121], v[126:127], 1.0 op_sel_hi:[1,0]
	v_rcp_f32_e32 v108, v108
	v_rcp_f32_e32 v120, v120
	v_rcp_f32_e32 v121, v121
	v_rcp_f32_e32 v109, v109
	v_pk_mul_f32 v[110:111], v[116:117], v[120:121] op_sel_hi:[0,1]
	v_pk_mul_f32 v[104:105], v[104:105], v[110:111]
	v_pk_mul_f32 v[110:111], v[100:101], v[118:119] op_sel_hi:[1,0]
	v_pk_mul_f32 v[108:109], v[116:117], v[108:109] op_sel_hi:[0,1]
	v_exp_f32_e32 v110, v110
	v_exp_f32_e32 v111, v111
	v_pk_mul_f32 v[106:107], v[106:107], v[108:109]
	v_pk_mul_f32 v[108:109], v[102:103], v[118:119] op_sel_hi:[1,0]
	v_cvt_pk_bf16_f32 v104, v104, v105
	v_cvt_pk_bf16_f32 v105, v106, v107
	v_pk_add_f32 v[106:107], v[110:111], 1.0 op_sel_hi:[1,0]
	v_exp_f32_e32 v108, v108
	v_exp_f32_e32 v109, v109
	v_rcp_f32_e32 v106, v106
	v_rcp_f32_e32 v107, v107
	v_pk_add_f32 v[100:101], v[108:109], 1.0 op_sel_hi:[1,0]
	s_nop 0
	v_rcp_f32_e32 v100, v100
	v_rcp_f32_e32 v101, v101
	v_pk_mul_f32 v[102:103], v[116:117], v[106:107] op_sel_hi:[0,1]
	v_pk_mul_f32 v[96:97], v[96:97], v[102:103]
	s_nop 0
	v_cvt_pk_bf16_f32 v106, v96, v97
	v_pk_mul_f32 v[96:97], v[116:117], v[100:101] op_sel_hi:[0,1]
	v_pk_mul_f32 v[96:97], v[98:99], v[96:97]
	s_nop 0
	v_cvt_pk_bf16_f32 v107, v96, v97
	v_fmamk_f32 v96, v145, 0x3a800000, v152
	v_rsq_f32_e32 v99, v96
	v_or_b32_e32 v96, 16, v144
	v_mad_i64_i32 v[96:97], s[38:39], v96, s59, v[112:113]
	v_mul_f32_e32 v98, 0xbfb8aa3b, v99
	v_pk_mul_f32 v[100:101], v[92:93], v[98:99] op_sel_hi:[1,0]
	v_pk_mul_f32 v[92:93], v[94:95], v[98:99] op_sel_hi:[1,0]
	v_exp_f32_e32 v100, v100
	v_exp_f32_e32 v101, v101
	v_exp_f32_e32 v92, v92
	v_exp_f32_e32 v93, v93
	v_lshl_add_u64 v[96:97], v[96:97], 0, v[114:115]
	v_pk_add_f32 v[100:101], v[100:101], 1.0 op_sel_hi:[1,0]
	global_store_dwordx4 v[96:97], v[104:107], off
	v_rcp_f32_e32 v100, v100
	v_rcp_f32_e32 v101, v101
	v_pk_add_f32 v[92:93], v[92:93], 1.0 op_sel_hi:[1,0]
	v_mul_f32_e32 v96, v99, v99
	v_rcp_f32_e32 v92, v92
	v_rcp_f32_e32 v93, v93
	v_pk_mul_f32 v[94:95], v[96:97], v[100:101] op_sel_hi:[0,1]
	v_pk_mul_f32 v[88:89], v[88:89], v[94:95]
	v_pk_mul_f32 v[94:95], v[84:85], v[98:99] op_sel_hi:[1,0]
	v_pk_mul_f32 v[92:93], v[96:97], v[92:93] op_sel_hi:[0,1]
	v_exp_f32_e32 v94, v94
	v_exp_f32_e32 v95, v95
	v_pk_mul_f32 v[90:91], v[90:91], v[92:93]
	v_pk_mul_f32 v[92:93], v[86:87], v[98:99] op_sel_hi:[1,0]
	v_cvt_pk_bf16_f32 v88, v88, v89
	v_cvt_pk_bf16_f32 v89, v90, v91
	v_pk_add_f32 v[90:91], v[94:95], 1.0 op_sel_hi:[1,0]
	v_exp_f32_e32 v92, v92
	v_exp_f32_e32 v93, v93
	v_rcp_f32_e32 v90, v90
	v_rcp_f32_e32 v91, v91
	v_pk_add_f32 v[84:85], v[92:93], 1.0 op_sel_hi:[1,0]
	s_nop 0
	v_rcp_f32_e32 v84, v84
	v_rcp_f32_e32 v85, v85
	v_pk_mul_f32 v[86:87], v[96:97], v[90:91] op_sel_hi:[0,1]
	v_pk_mul_f32 v[80:81], v[80:81], v[86:87]
	s_nop 0
	v_cvt_pk_bf16_f32 v90, v80, v81
	v_pk_mul_f32 v[80:81], v[96:97], v[84:85] op_sel_hi:[0,1]
	v_pk_mul_f32 v[80:81], v[82:83], v[80:81]
	s_nop 0
	v_cvt_pk_bf16_f32 v91, v80, v81
	v_fmamk_f32 v80, v153, 0x3a800000, v152
	v_rsq_f32_e32 v83, v80
	v_or_b32_e32 v80, 32, v144
	v_mad_i64_i32 v[80:81], s[38:39], v80, s59, v[112:113]
	v_mul_f32_e32 v82, 0xbfb8aa3b, v83
	v_pk_mul_f32 v[84:85], v[76:77], v[82:83] op_sel_hi:[1,0]
	v_pk_mul_f32 v[76:77], v[78:79], v[82:83] op_sel_hi:[1,0]
	v_exp_f32_e32 v84, v84
	v_exp_f32_e32 v85, v85
	v_exp_f32_e32 v76, v76
	v_exp_f32_e32 v77, v77
	v_lshl_add_u64 v[80:81], v[80:81], 0, v[114:115]
	v_pk_add_f32 v[84:85], v[84:85], 1.0 op_sel_hi:[1,0]
	global_store_dwordx4 v[80:81], v[88:91], off
	v_rcp_f32_e32 v84, v84
	v_rcp_f32_e32 v85, v85
	v_pk_add_f32 v[76:77], v[76:77], 1.0 op_sel_hi:[1,0]
	v_mul_f32_e32 v80, v83, v83
	v_rcp_f32_e32 v76, v76
	v_rcp_f32_e32 v77, v77
	v_pk_mul_f32 v[78:79], v[80:81], v[84:85] op_sel_hi:[0,1]
	v_pk_mul_f32 v[72:73], v[72:73], v[78:79]
	v_pk_mul_f32 v[78:79], v[68:69], v[82:83] op_sel_hi:[1,0]
	v_pk_mul_f32 v[76:77], v[80:81], v[76:77] op_sel_hi:[0,1]
	v_exp_f32_e32 v78, v78
	v_exp_f32_e32 v79, v79
	v_pk_mul_f32 v[74:75], v[74:75], v[76:77]
	v_pk_mul_f32 v[76:77], v[70:71], v[82:83] op_sel_hi:[1,0]
	v_cvt_pk_bf16_f32 v72, v72, v73
	v_cvt_pk_bf16_f32 v73, v74, v75
; __device__ __forceinline__ unsigned cvt_pk_bf16(float lo, float hi) { unsigned r; asm volatile("v_cvt_pk_bf16_f32 %0, %1, %2" : "=v"(r) : "v"(lo), "v"(hi)); return r; }
; __device__ __forceinline__ unsigned silu_pk(f32x2 g, f32x2 u, float k1, float k2) {
;     const f32x2 t = g * k1; f32x2 ex; ex.x = __builtin_amdgcn_exp2f(t.x); ex.y = __builtin_amdgcn_exp2f(t.y);
;     const f32x2 d = ex + 1.0f; f32x2 r; r.x = __builtin_amdgcn_rcpf(d.x); r.y = __builtin_amdgcn_rcpf(d.y);
;     const f32x2 o = (g * u) * (r * k2);
;     return cvt_pk_bf16(o.x, o.y);
;     __device__ __forceinline__ void operator()(const f32x4 (&acc)[2][2][4][2], const Unit& u, int wr, int wc, int fr, int fq) const {
;     ...
;             for (int m = 0; m < 4; ++m) {
;                 const int row = row0 + ai * HALF + m * 16; const float rs = __builtin_amdgcn_rsqf(ssq[ai][m] * (1.0f / 1024.0f) + 1e-6f);
;                 const float k1 = -1.4426950408889634f * rs, k2 = rs * rs;
;                 u32x4 w;
; #pragma unroll
;                 for (int n = 0; n < 2; ++n) {
;                     const f32x4 gv = acc[ai][0][m][n], uv = acc[ai][1][m][n];
;                     const unsigned lo = silu_pk((f32x2){gv[0], gv[1]}, (f32x2){uv[0], uv[1]}, k1, k2), hi = silu_pk((f32x2){gv[2], gv[3]}, (f32x2){uv[2], uv[3]}, k1, k2);
;                     if (n == 0) { w.x = lo; w.y = hi; } else { w.z = lo; w.w = hi; }
;                 }
;                 *(u32x4*)(O + (size_t)row * ldc + col0) = w;
	v_pk_add_f32 v[74:75], v[78:79], 1.0 op_sel_hi:[1,0]
	v_exp_f32_e32 v76, v76
	v_exp_f32_e32 v77, v77
	v_rcp_f32_e32 v74, v74
	v_rcp_f32_e32 v75, v75
	v_pk_add_f32 v[68:69], v[76:77], 1.0 op_sel_hi:[1,0]
	s_nop 0
	v_rcp_f32_e32 v68, v68
	v_rcp_f32_e32 v69, v69
	v_pk_mul_f32 v[70:71], v[80:81], v[74:75] op_sel_hi:[0,1]
	v_pk_mul_f32 v[64:65], v[64:65], v[70:71]
	s_nop 0
	v_cvt_pk_bf16_f32 v74, v64, v65
	v_pk_mul_f32 v[64:65], v[80:81], v[68:69] op_sel_hi:[0,1]
	v_pk_mul_f32 v[64:65], v[66:67], v[64:65]
	s_nop 0
	v_cvt_pk_bf16_f32 v75, v64, v65
	v_fmamk_f32 v65, v155, 0x3a800000, v152
	v_rsq_f32_e32 v67, v65
	v_or_b32_e32 v64, 48, v144
	v_mad_i64_i32 v[64:65], s[38:39], v64, s59, v[112:113]
	v_mul_f32_e32 v66, 0xbfb8aa3b, v67
	v_pk_mul_f32 v[68:69], v[60:61], v[66:67] op_sel_hi:[1,0]
	v_pk_mul_f32 v[60:61], v[62:63], v[66:67] op_sel_hi:[1,0]
	v_exp_f32_e32 v68, v68
	v_exp_f32_e32 v69, v69
	v_exp_f32_e32 v60, v60
	v_exp_f32_e32 v61, v61
	v_lshl_add_u64 v[64:65], v[64:65], 0, v[114:115]
	v_pk_add_f32 v[68:69], v[68:69], 1.0 op_sel_hi:[1,0]
	global_store_dwordx4 v[64:65], v[72:75], off
	v_rcp_f32_e32 v68, v68
	v_rcp_f32_e32 v69, v69
	v_pk_add_f32 v[60:61], v[60:61], 1.0 op_sel_hi:[1,0]
	v_add_u32_e32 v65, 0x80, v144
	v_rcp_f32_e32 v60, v60
	v_rcp_f32_e32 v61, v61
	v_mul_f32_e32 v64, v67, v67
	v_pk_mul_f32 v[62:63], v[64:65], v[68:69] op_sel_hi:[0,1]
	v_pk_mul_f32 v[56:57], v[56:57], v[62:63]
	v_pk_mul_f32 v[62:63], v[52:53], v[66:67] op_sel_hi:[1,0]
	v_pk_mul_f32 v[60:61], v[64:65], v[60:61] op_sel_hi:[0,1]
	v_exp_f32_e32 v62, v62
	v_exp_f32_e32 v63, v63
	v_pk_mul_f32 v[58:59], v[58:59], v[60:61]
	v_pk_mul_f32 v[60:61], v[54:55], v[66:67] op_sel_hi:[1,0]
	v_cvt_pk_bf16_f32 v56, v56, v57
	v_cvt_pk_bf16_f32 v57, v58, v59
	v_pk_add_f32 v[58:59], v[62:63], 1.0 op_sel_hi:[1,0]
	v_exp_f32_e32 v60, v60
	v_exp_f32_e32 v61, v61
	v_rcp_f32_e32 v58, v58
	v_rcp_f32_e32 v59, v59
	v_pk_add_f32 v[52:53], v[60:61], 1.0 op_sel_hi:[1,0]
	s_nop 0
	v_rcp_f32_e32 v52, v52
	v_rcp_f32_e32 v53, v53
	v_pk_mul_f32 v[54:55], v[64:65], v[58:59] op_sel_hi:[0,1]
	v_pk_mul_f32 v[48:49], v[48:49], v[54:55]
	s_nop 0
	v_cvt_pk_bf16_f32 v58, v48, v49
	v_pk_mul_f32 v[48:49], v[64:65], v[52:53] op_sel_hi:[0,1]
	v_pk_mul_f32 v[48:49], v[50:51], v[48:49]
	v_fmamk_f32 v50, v160, 0x3a800000, v152
	v_rsq_f32_e32 v51, v50
	v_cvt_pk_bf16_f32 v59, v48, v49
	v_mad_i64_i32 v[48:49], s[38:39], v65, s59, v[112:113]
	v_mul_f32_e32 v50, 0xbfb8aa3b, v51
	v_pk_mul_f32 v[52:53], v[44:45], v[50:51] op_sel_hi:[1,0]
	v_pk_mul_f32 v[44:45], v[46:47], v[50:51] op_sel_hi:[1,0]
	v_exp_f32_e32 v52, v52
	v_exp_f32_e32 v53, v53
	v_exp_f32_e32 v44, v44
	v_exp_f32_e32 v45, v45
	v_lshl_add_u64 v[48:49], v[48:49], 0, v[114:115]
	v_pk_add_f32 v[52:53], v[52:53], 1.0 op_sel_hi:[1,0]
	global_store_dwordx4 v[48:49], v[56:59], off
	v_rcp_f32_e32 v52, v52
	v_rcp_f32_e32 v53, v53
	v_pk_add_f32 v[44:45], v[44:45], 1.0 op_sel_hi:[1,0]
	v_mul_f32_e32 v48, v51, v51
	v_rcp_f32_e32 v44, v44
	v_rcp_f32_e32 v45, v45
	v_pk_mul_f32 v[46:47], v[48:49], v[52:53] op_sel_hi:[0,1]
	v_pk_mul_f32 v[40:41], v[40:41], v[46:47]
	v_pk_mul_f32 v[46:47], v[36:37], v[50:51] op_sel_hi:[1,0]
	v_pk_mul_f32 v[44:45], v[48:49], v[44:45] op_sel_hi:[0,1]
	v_exp_f32_e32 v46, v46
	v_exp_f32_e32 v47, v47
	v_pk_mul_f32 v[42:43], v[42:43], v[44:45]
	v_pk_mul_f32 v[44:45], v[38:39], v[50:51] op_sel_hi:[1,0]
	v_cvt_pk_bf16_f32 v40, v40, v41
	v_cvt_pk_bf16_f32 v41, v42, v43
	v_pk_add_f32 v[42:43], v[46:47], 1.0 op_sel_hi:[1,0]
	v_exp_f32_e32 v44, v44
	v_exp_f32_e32 v45, v45
	v_rcp_f32_e32 v42, v42
	v_rcp_f32_e32 v43, v43
	v_pk_add_f32 v[36:37], v[44:45], 1.0 op_sel_hi:[1,0]
	s_nop 0
	v_rcp_f32_e32 v36, v36
	v_rcp_f32_e32 v37, v37
	v_pk_mul_f32 v[38:39], v[48:49], v[42:43] op_sel_hi:[0,1]
	v_pk_mul_f32 v[32:33], v[32:33], v[38:39]
	s_nop 0
	v_cvt_pk_bf16_f32 v42, v32, v33
; __device__ __forceinline__ unsigned cvt_pk_bf16(float lo, float hi) { unsigned r; asm volatile("v_cvt_pk_bf16_f32 %0, %1, %2" : "=v"(r) : "v"(lo), "v"(hi)); return r; }
; #define PG8_BAR __builtin_amdgcn_s_barrier()
; __device__ __forceinline__ unsigned silu_pk(f32x2 g, f32x2 u, float k1, float k2) {
;     const f32x2 t = g * k1; f32x2 ex; ex.x = __builtin_amdgcn_exp2f(t.x); ex.y = __builtin_amdgcn_exp2f(t.y);
;     const f32x2 d = ex + 1.0f; f32x2 r; r.x = __builtin_amdgcn_rcpf(d.x); r.y = __builtin_amdgcn_rcpf(d.y);
;     const f32x2 o = (g * u) * (r * k2);
;     return cvt_pk_bf16(o.x, o.y);
;     __device__ __forceinline__ void operator()(const f32x4 (&acc)[2][2][4][2], const Unit& u, int wr, int wc, int fr, int fq) const {
;     ...
;             for (int m = 0; m < 4; ++m) {
;                 const int row = row0 + ai * HALF + m * 16; const float rs = __builtin_amdgcn_rsqf(ssq[ai][m] * (1.0f / 1024.0f) + 1e-6f);
;                 const float k1 = -1.4426950408889634f * rs, k2 = rs * rs;
;                 u32x4 w;
; #pragma unroll
;                 for (int n = 0; n < 2; ++n) {
;                     const f32x4 gv = acc[ai][0][m][n], uv = acc[ai][1][m][n];
;                     const unsigned lo = silu_pk((f32x2){gv[0], gv[1]}, (f32x2){uv[0], uv[1]}, k1, k2), hi = silu_pk((f32x2){gv[2], gv[3]}, (f32x2){uv[2], uv[3]}, k1, k2);
;                     if (n == 0) { w.x = lo; w.y = hi; } else { w.z = lo; w.w = hi; }
;                 }
;                 *(u32x4*)(O + (size_t)row * ldc + col0) = w;
; template <class Epi, class Sched, bool ALIGN_EPI = false, bool SP2 = false>
; __device__ __forceinline__ void gemm_phase(PG8_LAS unsigned char* lds, const Gemm g, const Sched& S, const Epi& E) {
;     ...
;         if (!has_next) break;
; #pragma unroll
;         for (int a = 0; a < 2; ++a)
; #pragma unroll
;             for (int b = 0; b < 2; ++b)
; #pragma unroll
;                 for (int m = 0; m < 4; ++m)
; #pragma unroll
;                     for (int n = 0; n < 2; ++n) acc[a][b][m][n] = (f32x4){0.f, 0.f, 0.f, 0.f};
;         cur = nxt; cA = nA; cB = nB; ++ui;
;         if constexpr (ALIGN_EPI) { if (wr == 1) PG8_BAR; }
	v_pk_mul_f32 v[32:33], v[48:49], v[36:37] op_sel_hi:[0,1]
	v_pk_mul_f32 v[32:33], v[34:35], v[32:33]
	s_nop 0
	v_cvt_pk_bf16_f32 v43, v32, v33
	v_fmamk_f32 v32, v125, 0x3a800000, v152
	v_rsq_f32_e32 v35, v32
	v_add_u32_e32 v32, 0x90, v144
	v_mad_i64_i32 v[32:33], s[38:39], v32, s59, v[112:113]
	v_mul_f32_e32 v34, 0xbfb8aa3b, v35
	v_pk_mul_f32 v[36:37], v[28:29], v[34:35] op_sel_hi:[1,0]
	v_pk_mul_f32 v[28:29], v[30:31], v[34:35] op_sel_hi:[1,0]
	v_exp_f32_e32 v36, v36
	v_exp_f32_e32 v37, v37
	v_exp_f32_e32 v28, v28
	v_exp_f32_e32 v29, v29
	v_lshl_add_u64 v[32:33], v[32:33], 0, v[114:115]
	v_pk_add_f32 v[36:37], v[36:37], 1.0 op_sel_hi:[1,0]
	global_store_dwordx4 v[32:33], v[40:43], off
	v_rcp_f32_e32 v36, v36
	v_rcp_f32_e32 v37, v37
	v_pk_add_f32 v[28:29], v[28:29], 1.0 op_sel_hi:[1,0]
	v_mul_f32_e32 v32, v35, v35
	v_rcp_f32_e32 v28, v28
	v_rcp_f32_e32 v29, v29
	v_pk_mul_f32 v[30:31], v[32:33], v[36:37] op_sel_hi:[0,1]
	v_pk_mul_f32 v[24:25], v[24:25], v[30:31]
	v_pk_mul_f32 v[30:31], v[20:21], v[34:35] op_sel_hi:[1,0]
	v_pk_mul_f32 v[28:29], v[32:33], v[28:29] op_sel_hi:[0,1]
	v_exp_f32_e32 v30, v30
	v_exp_f32_e32 v31, v31
	v_pk_mul_f32 v[26:27], v[26:27], v[28:29]
	v_pk_mul_f32 v[28:29], v[22:23], v[34:35] op_sel_hi:[1,0]
	v_cvt_pk_bf16_f32 v24, v24, v25
	v_cvt_pk_bf16_f32 v25, v26, v27
	v_pk_add_f32 v[26:27], v[30:31], 1.0 op_sel_hi:[1,0]
	v_exp_f32_e32 v28, v28
	v_exp_f32_e32 v29, v29
	v_rcp_f32_e32 v26, v26
	v_rcp_f32_e32 v27, v27
	v_pk_add_f32 v[20:21], v[28:29], 1.0 op_sel_hi:[1,0]
	s_nop 0
	v_rcp_f32_e32 v20, v20
	v_rcp_f32_e32 v21, v21
	v_pk_mul_f32 v[22:23], v[32:33], v[26:27] op_sel_hi:[0,1]
	v_pk_mul_f32 v[16:17], v[16:17], v[22:23]
	s_nop 0
	v_cvt_pk_bf16_f32 v26, v16, v17
	v_pk_mul_f32 v[16:17], v[32:33], v[20:21] op_sel_hi:[0,1]
	v_pk_mul_f32 v[16:17], v[18:19], v[16:17]
	s_nop 0
	v_cvt_pk_bf16_f32 v27, v16, v17
	v_fmamk_f32 v16, v124, 0x3a800000, v152
	v_rsq_f32_e32 v19, v16
	v_add_u32_e32 v16, 0xa0, v144
	v_mad_i64_i32 v[16:17], s[38:39], v16, s59, v[112:113]
	v_mul_f32_e32 v18, 0xbfb8aa3b, v19
	v_pk_mul_f32 v[20:21], v[12:13], v[18:19] op_sel_hi:[1,0]
	v_pk_mul_f32 v[12:13], v[14:15], v[18:19] op_sel_hi:[1,0]
	v_exp_f32_e32 v20, v20
	v_exp_f32_e32 v21, v21
	v_exp_f32_e32 v12, v12
	v_exp_f32_e32 v13, v13
	v_lshl_add_u64 v[16:17], v[16:17], 0, v[114:115]
	v_pk_add_f32 v[20:21], v[20:21], 1.0 op_sel_hi:[1,0]
	global_store_dwordx4 v[16:17], v[24:27], off
	v_rcp_f32_e32 v20, v20
	v_rcp_f32_e32 v21, v21
	v_pk_add_f32 v[12:13], v[12:13], 1.0 op_sel_hi:[1,0]
	v_mul_f32_e32 v16, v19, v19
	v_rcp_f32_e32 v12, v12
	v_rcp_f32_e32 v13, v13
	v_pk_mul_f32 v[14:15], v[16:17], v[20:21] op_sel_hi:[0,1]
	v_pk_mul_f32 v[8:9], v[8:9], v[14:15]
	v_pk_mul_f32 v[14:15], v[4:5], v[18:19] op_sel_hi:[1,0]
	v_pk_mul_f32 v[12:13], v[16:17], v[12:13] op_sel_hi:[0,1]
	v_exp_f32_e32 v14, v14
	v_exp_f32_e32 v15, v15
	v_pk_mul_f32 v[10:11], v[10:11], v[12:13]
	v_pk_mul_f32 v[12:13], v[6:7], v[18:19] op_sel_hi:[1,0]
	v_cvt_pk_bf16_f32 v8, v8, v9
	v_cvt_pk_bf16_f32 v9, v10, v11
	v_pk_add_f32 v[10:11], v[14:15], 1.0 op_sel_hi:[1,0]
	v_exp_f32_e32 v12, v12
	v_exp_f32_e32 v13, v13
	v_rcp_f32_e32 v10, v10
	v_rcp_f32_e32 v11, v11
	v_pk_add_f32 v[4:5], v[12:13], 1.0 op_sel_hi:[1,0]
	s_nop 0
	v_rcp_f32_e32 v4, v4
	v_rcp_f32_e32 v5, v5
	v_pk_mul_f32 v[6:7], v[16:17], v[10:11] op_sel_hi:[0,1]
	v_pk_mul_f32 v[0:1], v[0:1], v[6:7]
	s_nop 0
	v_cvt_pk_bf16_f32 v10, v0, v1
	v_pk_mul_f32 v[0:1], v[16:17], v[4:5] op_sel_hi:[0,1]
	v_pk_mul_f32 v[0:1], v[2:3], v[0:1]
	s_nop 0
	v_cvt_pk_bf16_f32 v11, v0, v1
	v_add_u32_e32 v0, 0xb0, v144
	v_mad_i64_i32 v[0:1], s[38:39], v0, s59, v[112:113]
	v_lshl_add_u64 v[0:1], v[0:1], 0, v[114:115]
	global_store_dwordx4 v[0:1], v[8:11], off
	s_cbranch_vccnz .LBB0_1190
	s_andn2_b64 vcc, exec, s[6:7]
	s_cbranch_vccnz .LBB0_1189
	s_barrier
	s_branch .LBB0_1189
